# four rows in flight in P1, P7, P11 streaming loops + Q-load deserialize
# speedup vs baseline: 1.0103x; 1.0023x over previous
; __device__ __forceinline__ unsigned cvtpk(float lo, float hi) { unsigned r; asm volatile("v_cvt_pk_bf16_f32 %0, %1, %2" : "=v"(r) : "v"(lo), "v"(hi)); return r; }
; __device__ __forceinline__ void modnorm_phase(const Ctx& X, const float* src_p, const float* src_s, const float* g, const float* mod, int sh_off, int sc_off, bf16_t* H) {
;     ...
;         for (int r = 0; r < 16; ++r) {
;             const float* xr = src + (size_t)(t0 + r) * DM + X.lane * 4;
;             f32x4 v[4]; float ss = 0.f;
; #pragma unroll
;             for (int j = 0; j < 4; ++j) { v[j] = *(const f32x4*)(xr + 256 * j); ss += (v[j].x * v[j].x + v[j].y * v[j].y) + (v[j].z * v[j].z + v[j].w * v[j].w); }
;             const float rstd = rsqrtf(wave_sum(ss) * (1.f / DM) + EPS);
;             bf16_t* orow = H + (size_t)(t0 + r) * DM + X.lane * 4;
; #pragma unroll
;             for (int j = 0; j < 4; ++j) { const f32x4 o = v[j] * rstd * gs[j] + sh[j]; u32x2 w; w.x = cvtpk(o.x, o.y); w.y = cvtpk(o.z, o.w); *(u32x2*)(orow + 256 * j) = w; }
.LBB0_71:
	s_add_i32 s6, s3, s13
	s_ashr_i32 s7, s6, 31
	s_lshl_b64 s[14:15], s[6:7], 12
	v_lshl_add_u64 v[58:59], v[22:23], 0, s[14:15]
	global_load_dwordx4 v[46:49], v[58:59], off
	global_load_dwordx4 v[50:53], v[58:59], off offset:1024
	global_load_dwordx4 v[54:57], v[58:59], off offset:3072
	s_nop 0
	global_load_dwordx4 v[58:61], v[58:59], off offset:2048
	v_mov_b32_e32 v77, 0
	v_mov_b32_e32 v45, 0
	s_add_i32 s0, s6, 1
	s_lshl_b64 s[6:7], s[6:7], 11
	s_ashr_i32 s1, s0, 31
	v_lshl_add_u64 v[62:63], v[18:19], 0, s[6:7]
	s_lshl_b64 s[6:7], s[0:1], 12
	v_lshl_add_u64 v[64:65], v[22:23], 0, s[6:7]
	s_lshl_b64 s[0:1], s[0:1], 11
	global_load_dwordx4 v[84:87], v[64:65], off
	global_load_dwordx4 v[88:91], v[64:65], off offset:1024
	global_load_dwordx4 v[92:95], v[64:65], off offset:2048
	global_load_dwordx4 v[96:99], v[64:65], off offset:3072
	s_add_i32 s98, s3, s13
	s_add_i32 s98, s98, 2
	s_mov_b32 s99, 0
	s_lshl_b64 s[98:99], s[98:99], 12
	v_lshl_add_u64 v[132:133], v[22:23], 0, s[98:99]
	s_nop 0
	v_add_co_u32_e32 v134, vcc, 0x1000, v132
	s_nop 1
	v_addc_co_u32_e32 v135, vcc, 0, v133, vcc
	global_load_dwordx4 v[100:103], v[132:133], off
	global_load_dwordx4 v[104:107], v[132:133], off offset:1024
	global_load_dwordx4 v[108:111], v[132:133], off offset:3072
	global_load_dwordx4 v[112:115], v[132:133], off offset:2048
	global_load_dwordx4 v[116:119], v[134:135], off
	global_load_dwordx4 v[120:123], v[134:135], off offset:1024
	global_load_dwordx4 v[124:127], v[134:135], off offset:2048
	global_load_dwordx4 v[128:131], v[134:135], off offset:3072
	s_add_i32 s13, s13, 2
	s_cmp_eq_u32 s13, 16
	s_waitcnt vmcnt(15)
	v_pk_mul_f32 v[66:67], v[48:49], v[48:49]
	v_pk_mul_f32 v[68:69], v[46:47], v[46:47]
	s_waitcnt vmcnt(14)
	v_pk_mul_f32 v[70:71], v[52:53], v[52:53]
	v_pk_mul_f32 v[72:73], v[50:51], v[50:51]
	v_pk_mov_b32 v[78:79], v[68:69], v[66:67] op_sel:[1,0]
	v_mov_b32_e32 v69, v67
	v_pk_mov_b32 v[66:67], v[72:73], v[70:71] op_sel:[1,0]
	v_mov_b32_e32 v73, v71
	s_waitcnt vmcnt(12)
	v_mul_f32_e32 v74, v59, v59
	v_mul_f32_e32 v76, v61, v61
	v_pk_add_f32 v[68:69], v[78:79], v[68:69]
	v_pk_add_f32 v[66:67], v[66:67], v[72:73]
	v_mul_f32_e32 v80, v54, v54
	v_mul_f32_e32 v81, v55, v55
	v_mul_f32_e32 v82, v56, v56
	v_mul_f32_e32 v83, v57, v57
	v_pk_fma_f32 v[70:71], v[58:59], v[58:59], v[74:75] op_sel_hi:[1,1,0]
	v_pk_fma_f32 v[74:75], v[60:61], v[60:61], v[76:77] op_sel_hi:[1,1,0]
	v_pk_add_f32 v[68:69], v[68:69], v[68:69] op_sel:[0,1] op_sel_hi:[1,0]
	v_pk_add_f32 v[66:67], v[66:67], v[66:67] op_sel:[0,1] op_sel_hi:[1,0]
	v_mov_b32_e32 v71, v82
	v_mov_b32_e32 v75, v83
	v_mov_b32_e32 v69, v80
	v_mov_b32_e32 v67, v81
	v_pk_add_f32 v[70:71], v[70:71], v[74:75]
	v_pk_add_f32 v[66:67], v[68:69], v[66:67]
	v_mov_b32_e32 v75, 0
	v_pk_add_f32 v[66:67], v[66:67], v[70:71]
	s_nop 0
	v_add_f32_e32 v66, v66, v67
	s_nop 1
	v_add_f32_dpp v66, v66, v66 quad_perm:[1,0,3,2] row_mask:0xf bank_mask:0xf bound_ctrl:1
	s_nop 1
	v_add_f32_dpp v66, v66, v66 quad_perm:[2,3,0,1] row_mask:0xf bank_mask:0xf bound_ctrl:1
	s_nop 1
	v_add_f32_dpp v66, v66, v66 row_half_mirror row_mask:0xf bank_mask:0xf bound_ctrl:1
	s_nop 1
	v_add_f32_dpp v66, v66, v66 row_mirror row_mask:0xf bank_mask:0xf bound_ctrl:1
	s_nop 1
	v_mov_b32_dpp v45, v66 row_bcast:15 row_mask:0xa bank_mask:0xf
	v_add_f32_e32 v45, v66, v45
	s_nop 1
	v_mov_b32_dpp v77, v45 row_bcast:31 row_mask:0xc bank_mask:0xf
	v_add_f32_e32 v45, v45, v77
	s_nop 0
	v_readlane_b32 s6, v45, 63
	s_nop 1
	v_fma_f32 v45, s6, v44, v43
	v_mul_f32_e32 v66, 0x4b800000, v45
	v_cmp_gt_f32_e32 vcc, s11, v45
	s_nop 1
	v_cndmask_b32_e32 v45, v45, v66, vcc
	v_rsq_f32_e32 v45, v45
	s_nop 0
	v_mul_f32_e32 v66, 0x45800000, v45
	v_cndmask_b32_e32 v66, v45, v66, vcc
	v_pk_mul_f32 v[46:47], v[46:47], v[66:67] op_sel_hi:[1,0]
	v_pk_mul_f32 v[48:49], v[48:49], v[66:67] op_sel_hi:[1,0]
	v_pk_fma_f32 v[46:47], v[26:27], v[46:47], v[0:1]
	v_pk_mul_f32 v[50:51], v[50:51], v[66:67] op_sel_hi:[1,0]
	v_pk_mul_f32 v[52:53], v[52:53], v[66:67] op_sel_hi:[1,0]
	v_pk_fma_f32 v[48:49], v[24:25], v[48:49], v[2:3]
	v_cvt_pk_bf16_f32 v46, v46, v47
	v_pk_mul_f32 v[58:59], v[58:59], v[66:67] op_sel_hi:[1,0]
	v_cvt_pk_bf16_f32 v47, v48, v49
	v_pk_mul_f32 v[60:61], v[60:61], v[66:67] op_sel_hi:[1,0]
	v_pk_fma_f32 v[52:53], v[28:29], v[52:53], v[6:7]
	v_pk_fma_f32 v[50:51], v[30:31], v[50:51], v[4:5]
	global_store_dwordx2 v[62:63], v[46:47], off
	v_cvt_pk_bf16_f32 v46, v50, v51
	v_cvt_pk_bf16_f32 v47, v52, v53
	v_pk_mul_f32 v[54:55], v[54:55], v[66:67] op_sel_hi:[1,0]
	v_pk_mul_f32 v[56:57], v[56:57], v[66:67] op_sel_hi:[1,0]
	v_pk_fma_f32 v[60:61], v[32:33], v[60:61], v[10:11]
	v_pk_fma_f32 v[58:59], v[34:35], v[58:59], v[8:9]
	global_store_dwordx2 v[62:63], v[46:47], off offset:512
	v_cvt_pk_bf16_f32 v46, v58, v59
	v_cvt_pk_bf16_f32 v47, v60, v61
	v_pk_fma_f32 v[56:57], v[36:37], v[56:57], v[14:15]
	v_pk_fma_f32 v[54:55], v[38:39], v[54:55], v[12:13]
	global_store_dwordx2 v[62:63], v[46:47], off offset:1024
	v_cvt_pk_bf16_f32 v46, v54, v55
	v_cvt_pk_bf16_f32 v47, v56, v57
	global_store_dwordx2 v[62:63], v[46:47], off offset:1536
	v_mov_b32_e32 v45, 0
	v_lshl_add_u64 v[62:63], v[18:19], 0, s[0:1]
	s_waitcnt vmcnt(15)
	v_pk_mul_f32 v[64:65], v[86:87], v[86:87]
	v_pk_mul_f32 v[66:67], v[84:85], v[84:85]
	s_waitcnt vmcnt(14)
	v_pk_mul_f32 v[68:69], v[90:91], v[90:91]
	v_pk_mul_f32 v[70:71], v[88:89], v[88:89]
	v_pk_mov_b32 v[76:77], v[66:67], v[64:65] op_sel:[1,0]
	v_mov_b32_e32 v67, v65
	v_pk_mov_b32 v[64:65], v[70:71], v[68:69] op_sel:[1,0]
	v_mov_b32_e32 v71, v69
	s_waitcnt vmcnt(13)
	v_mul_f32_e32 v72, v93, v93
	v_mul_f32_e32 v74, v95, v95
	v_pk_add_f32 v[66:67], v[76:77], v[66:67]
	v_pk_add_f32 v[64:65], v[64:65], v[70:71]
	s_waitcnt vmcnt(12)
; __device__ __forceinline__ unsigned cvtpk(float lo, float hi) { unsigned r; asm volatile("v_cvt_pk_bf16_f32 %0, %1, %2" : "=v"(r) : "v"(lo), "v"(hi)); return r; }
; __device__ __forceinline__ void modnorm_phase(const Ctx& X, const float* src_p, const float* src_s, const float* g, const float* mod, int sh_off, int sc_off, bf16_t* H) {
;     ...
;         for (int r = 0; r < 16; ++r) {
;             const float* xr = src + (size_t)(t0 + r) * DM + X.lane * 4;
;             f32x4 v[4]; float ss = 0.f;
; #pragma unroll
;             for (int j = 0; j < 4; ++j) { v[j] = *(const f32x4*)(xr + 256 * j); ss += (v[j].x * v[j].x + v[j].y * v[j].y) + (v[j].z * v[j].z + v[j].w * v[j].w); }
;             const float rstd = rsqrtf(wave_sum(ss) * (1.f / DM) + EPS);
;             bf16_t* orow = H + (size_t)(t0 + r) * DM + X.lane * 4;
; #pragma unroll
;             for (int j = 0; j < 4; ++j) { const f32x4 o = v[j] * rstd * gs[j] + sh[j]; u32x2 w; w.x = cvtpk(o.x, o.y); w.y = cvtpk(o.z, o.w); *(u32x2*)(orow + 256 * j) = w; }
	v_mul_f32_e32 v78, v96, v96
	v_mul_f32_e32 v79, v97, v97
	v_mul_f32_e32 v80, v98, v98
	v_mul_f32_e32 v81, v99, v99
	v_pk_fma_f32 v[68:69], v[92:93], v[92:93], v[72:73] op_sel_hi:[1,1,0]
	v_pk_fma_f32 v[72:73], v[94:95], v[94:95], v[74:75] op_sel_hi:[1,1,0]
	v_pk_add_f32 v[66:67], v[66:67], v[66:67] op_sel:[0,1] op_sel_hi:[1,0]
	v_pk_add_f32 v[64:65], v[64:65], v[64:65] op_sel:[0,1] op_sel_hi:[1,0]
	v_mov_b32_e32 v69, v80
	v_mov_b32_e32 v73, v81
	v_mov_b32_e32 v67, v78
	v_mov_b32_e32 v65, v79
	v_pk_add_f32 v[68:69], v[68:69], v[72:73]
	v_pk_add_f32 v[64:65], v[66:67], v[64:65]
	s_nop 0
	v_pk_add_f32 v[64:65], v[64:65], v[68:69]
	s_nop 0
	v_add_f32_e32 v64, v64, v65
	s_nop 1
	v_add_f32_dpp v64, v64, v64 quad_perm:[1,0,3,2] row_mask:0xf bank_mask:0xf bound_ctrl:1
	s_nop 1
	v_add_f32_dpp v64, v64, v64 quad_perm:[2,3,0,1] row_mask:0xf bank_mask:0xf bound_ctrl:1
	s_nop 1
	v_add_f32_dpp v64, v64, v64 row_half_mirror row_mask:0xf bank_mask:0xf bound_ctrl:1
	s_nop 1
	v_add_f32_dpp v64, v64, v64 row_mirror row_mask:0xf bank_mask:0xf bound_ctrl:1
	s_nop 1
	v_mov_b32_dpp v45, v64 row_bcast:15 row_mask:0xa bank_mask:0xf
	v_add_f32_e32 v45, v64, v45
	s_nop 1
	v_mov_b32_dpp v75, v45 row_bcast:31 row_mask:0xc bank_mask:0xf
	v_add_f32_e32 v45, v45, v75
	s_nop 0
	v_readlane_b32 s0, v45, 63
	s_nop 1
	v_fma_f32 v45, s0, v44, v43
	v_mul_f32_e32 v64, 0x4b800000, v45
	v_cmp_gt_f32_e32 vcc, s11, v45
	s_nop 1
	v_cndmask_b32_e32 v45, v45, v64, vcc
	v_rsq_f32_e32 v45, v45
	s_nop 0
	v_mul_f32_e32 v64, 0x45800000, v45
	v_cndmask_b32_e32 v64, v45, v64, vcc
	v_pk_mul_f32 v[84:85], v[84:85], v[64:65] op_sel_hi:[1,0]
	v_pk_mul_f32 v[86:87], v[86:87], v[64:65] op_sel_hi:[1,0]
	v_pk_fma_f32 v[84:85], v[26:27], v[84:85], v[0:1]
	v_pk_mul_f32 v[88:89], v[88:89], v[64:65] op_sel_hi:[1,0]
	v_pk_mul_f32 v[90:91], v[90:91], v[64:65] op_sel_hi:[1,0]
	v_pk_fma_f32 v[86:87], v[24:25], v[86:87], v[2:3]
	v_cvt_pk_bf16_f32 v84, v84, v85
	v_pk_mul_f32 v[92:93], v[92:93], v[64:65] op_sel_hi:[1,0]
	v_cvt_pk_bf16_f32 v85, v86, v87
	v_pk_mul_f32 v[94:95], v[94:95], v[64:65] op_sel_hi:[1,0]
	v_pk_fma_f32 v[90:91], v[28:29], v[90:91], v[6:7]
	v_pk_fma_f32 v[88:89], v[30:31], v[88:89], v[4:5]
	global_store_dwordx2 v[62:63], v[84:85], off
	v_cvt_pk_bf16_f32 v84, v88, v89
	v_cvt_pk_bf16_f32 v85, v90, v91
	v_pk_mul_f32 v[96:97], v[96:97], v[64:65] op_sel_hi:[1,0]
	v_pk_mul_f32 v[98:99], v[98:99], v[64:65] op_sel_hi:[1,0]
	v_pk_fma_f32 v[94:95], v[32:33], v[94:95], v[10:11]
	v_pk_fma_f32 v[92:93], v[34:35], v[92:93], v[8:9]
	global_store_dwordx2 v[62:63], v[84:85], off offset:512
	v_cvt_pk_bf16_f32 v84, v92, v93
	v_cvt_pk_bf16_f32 v85, v94, v95
	v_pk_fma_f32 v[98:99], v[36:37], v[98:99], v[14:15]
	v_pk_fma_f32 v[96:97], v[38:39], v[96:97], v[12:13]
	global_store_dwordx2 v[62:63], v[84:85], off offset:1024
	v_cvt_pk_bf16_f32 v84, v96, v97
	v_cvt_pk_bf16_f32 v85, v98, v99
	global_store_dwordx2 v[62:63], v[84:85], off offset:1536
	s_add_i32 s6, s3, s13
	s_ashr_i32 s7, s6, 31
	s_lshl_b64 s[14:15], s[6:7], 12
	s_nop 0
	v_mov_b32_e32 v77, 0
	v_mov_b32_e32 v45, 0
	s_add_i32 s0, s6, 1
	s_lshl_b64 s[6:7], s[6:7], 11
	s_ashr_i32 s1, s0, 31
	v_lshl_add_u64 v[62:63], v[18:19], 0, s[6:7]
	s_lshl_b64 s[6:7], s[0:1], 12
	v_lshl_add_u64 v[64:65], v[22:23], 0, s[6:7]
	s_lshl_b64 s[0:1], s[0:1], 11
	s_add_i32 s13, s13, 2
	s_cmp_eq_u32 s13, 16
	s_waitcnt vmcnt(15)
	v_pk_mul_f32 v[66:67], v[102:103], v[102:103]
	v_pk_mul_f32 v[68:69], v[100:101], v[100:101]
	s_waitcnt vmcnt(14)
	v_pk_mul_f32 v[70:71], v[106:107], v[106:107]
	v_pk_mul_f32 v[72:73], v[104:105], v[104:105]
	v_pk_mov_b32 v[78:79], v[68:69], v[66:67] op_sel:[1,0]
	v_mov_b32_e32 v69, v67
	v_pk_mov_b32 v[66:67], v[72:73], v[70:71] op_sel:[1,0]
	v_mov_b32_e32 v73, v71
	s_waitcnt vmcnt(12)
; __device__ __forceinline__ unsigned cvtpk(float lo, float hi) { unsigned r; asm volatile("v_cvt_pk_bf16_f32 %0, %1, %2" : "=v"(r) : "v"(lo), "v"(hi)); return r; }
; __device__ __forceinline__ void modnorm_phase(const Ctx& X, const float* src_p, const float* src_s, const float* g, const float* mod, int sh_off, int sc_off, bf16_t* H) {
;     ...
;         for (int r = 0; r < 16; ++r) {
;             const float* xr = src + (size_t)(t0 + r) * DM + X.lane * 4;
;             f32x4 v[4]; float ss = 0.f;
; #pragma unroll
;             for (int j = 0; j < 4; ++j) { v[j] = *(const f32x4*)(xr + 256 * j); ss += (v[j].x * v[j].x + v[j].y * v[j].y) + (v[j].z * v[j].z + v[j].w * v[j].w); }
;             const float rstd = rsqrtf(wave_sum(ss) * (1.f / DM) + EPS);
;             bf16_t* orow = H + (size_t)(t0 + r) * DM + X.lane * 4;
; #pragma unroll
;             for (int j = 0; j < 4; ++j) { const f32x4 o = v[j] * rstd * gs[j] + sh[j]; u32x2 w; w.x = cvtpk(o.x, o.y); w.y = cvtpk(o.z, o.w); *(u32x2*)(orow + 256 * j) = w; }
	v_mul_f32_e32 v74, v113, v113
	v_mul_f32_e32 v76, v115, v115
	v_pk_add_f32 v[68:69], v[78:79], v[68:69]
	v_pk_add_f32 v[66:67], v[66:67], v[72:73]
	v_mul_f32_e32 v80, v108, v108
	v_mul_f32_e32 v81, v109, v109
	v_mul_f32_e32 v82, v110, v110
	v_mul_f32_e32 v83, v111, v111
	v_pk_fma_f32 v[70:71], v[112:113], v[112:113], v[74:75] op_sel_hi:[1,1,0]
	v_pk_fma_f32 v[74:75], v[114:115], v[114:115], v[76:77] op_sel_hi:[1,1,0]
	v_pk_add_f32 v[68:69], v[68:69], v[68:69] op_sel:[0,1] op_sel_hi:[1,0]
	v_pk_add_f32 v[66:67], v[66:67], v[66:67] op_sel:[0,1] op_sel_hi:[1,0]
	v_mov_b32_e32 v71, v82
	v_mov_b32_e32 v75, v83
	v_mov_b32_e32 v69, v80
	v_mov_b32_e32 v67, v81
	v_pk_add_f32 v[70:71], v[70:71], v[74:75]
	v_pk_add_f32 v[66:67], v[68:69], v[66:67]
	v_mov_b32_e32 v75, 0
	v_pk_add_f32 v[66:67], v[66:67], v[70:71]
	s_nop 0
	v_add_f32_e32 v66, v66, v67
	s_nop 1
	v_add_f32_dpp v66, v66, v66 quad_perm:[1,0,3,2] row_mask:0xf bank_mask:0xf bound_ctrl:1
	s_nop 1
	v_add_f32_dpp v66, v66, v66 quad_perm:[2,3,0,1] row_mask:0xf bank_mask:0xf bound_ctrl:1
	s_nop 1
	v_add_f32_dpp v66, v66, v66 row_half_mirror row_mask:0xf bank_mask:0xf bound_ctrl:1
	s_nop 1
	v_add_f32_dpp v66, v66, v66 row_mirror row_mask:0xf bank_mask:0xf bound_ctrl:1
	s_nop 1
	v_mov_b32_dpp v45, v66 row_bcast:15 row_mask:0xa bank_mask:0xf
	v_add_f32_e32 v45, v66, v45
	s_nop 1
	v_mov_b32_dpp v77, v45 row_bcast:31 row_mask:0xc bank_mask:0xf
	v_add_f32_e32 v45, v45, v77
	s_nop 0
	v_readlane_b32 s6, v45, 63
	s_nop 1
	v_fma_f32 v45, s6, v44, v43
	v_mul_f32_e32 v66, 0x4b800000, v45
	v_cmp_gt_f32_e32 vcc, s11, v45
	s_nop 1
	v_cndmask_b32_e32 v45, v45, v66, vcc
	v_rsq_f32_e32 v45, v45
	s_nop 0
	v_mul_f32_e32 v66, 0x45800000, v45
	v_cndmask_b32_e32 v66, v45, v66, vcc
	v_pk_mul_f32 v[100:101], v[100:101], v[66:67] op_sel_hi:[1,0]
	v_pk_mul_f32 v[102:103], v[102:103], v[66:67] op_sel_hi:[1,0]
	v_pk_fma_f32 v[100:101], v[26:27], v[100:101], v[0:1]
	v_pk_mul_f32 v[104:105], v[104:105], v[66:67] op_sel_hi:[1,0]
	v_pk_mul_f32 v[106:107], v[106:107], v[66:67] op_sel_hi:[1,0]
	v_pk_fma_f32 v[102:103], v[24:25], v[102:103], v[2:3]
	v_cvt_pk_bf16_f32 v100, v100, v101
	v_pk_mul_f32 v[112:113], v[112:113], v[66:67] op_sel_hi:[1,0]
	v_cvt_pk_bf16_f32 v101, v102, v103
	v_pk_mul_f32 v[114:115], v[114:115], v[66:67] op_sel_hi:[1,0]
	v_pk_fma_f32 v[106:107], v[28:29], v[106:107], v[6:7]
	v_pk_fma_f32 v[104:105], v[30:31], v[104:105], v[4:5]
	global_store_dwordx2 v[62:63], v[100:101], off
	v_cvt_pk_bf16_f32 v100, v104, v105
	v_cvt_pk_bf16_f32 v101, v106, v107
	v_pk_mul_f32 v[108:109], v[108:109], v[66:67] op_sel_hi:[1,0]
	v_pk_mul_f32 v[110:111], v[110:111], v[66:67] op_sel_hi:[1,0]
	v_pk_fma_f32 v[114:115], v[32:33], v[114:115], v[10:11]
	v_pk_fma_f32 v[112:113], v[34:35], v[112:113], v[8:9]
	global_store_dwordx2 v[62:63], v[100:101], off offset:512
	v_cvt_pk_bf16_f32 v100, v112, v113
	v_cvt_pk_bf16_f32 v101, v114, v115
	v_pk_fma_f32 v[110:111], v[36:37], v[110:111], v[14:15]
	v_pk_fma_f32 v[108:109], v[38:39], v[108:109], v[12:13]
	global_store_dwordx2 v[62:63], v[100:101], off offset:1024
	v_cvt_pk_bf16_f32 v100, v108, v109
	v_cvt_pk_bf16_f32 v101, v110, v111
	global_store_dwordx2 v[62:63], v[100:101], off offset:1536
	v_mov_b32_e32 v45, 0
	v_lshl_add_u64 v[62:63], v[18:19], 0, s[0:1]
	s_waitcnt vmcnt(15)
	v_pk_mul_f32 v[64:65], v[118:119], v[118:119]
	v_pk_mul_f32 v[66:67], v[116:117], v[116:117]
	s_waitcnt vmcnt(14)
	v_pk_mul_f32 v[68:69], v[122:123], v[122:123]
	v_pk_mul_f32 v[70:71], v[120:121], v[120:121]
	v_pk_mov_b32 v[76:77], v[66:67], v[64:65] op_sel:[1,0]
	v_mov_b32_e32 v67, v65
	v_pk_mov_b32 v[64:65], v[70:71], v[68:69] op_sel:[1,0]
	v_mov_b32_e32 v71, v69
	s_waitcnt vmcnt(13)
	v_mul_f32_e32 v72, v125, v125
	v_mul_f32_e32 v74, v127, v127
	v_pk_add_f32 v[66:67], v[76:77], v[66:67]
	v_pk_add_f32 v[64:65], v[64:65], v[70:71]
	s_waitcnt vmcnt(12)
	v_mul_f32_e32 v78, v128, v128
	v_mul_f32_e32 v79, v129, v129
	v_mul_f32_e32 v80, v130, v130
	v_mul_f32_e32 v81, v131, v131
	v_pk_fma_f32 v[68:69], v[124:125], v[124:125], v[72:73] op_sel_hi:[1,1,0]
	v_pk_fma_f32 v[72:73], v[126:127], v[126:127], v[74:75] op_sel_hi:[1,1,0]
	v_pk_add_f32 v[66:67], v[66:67], v[66:67] op_sel:[0,1] op_sel_hi:[1,0]
	v_pk_add_f32 v[64:65], v[64:65], v[64:65] op_sel:[0,1] op_sel_hi:[1,0]
	v_mov_b32_e32 v69, v80
	v_mov_b32_e32 v73, v81
	v_mov_b32_e32 v67, v78
	v_mov_b32_e32 v65, v79
	v_pk_add_f32 v[68:69], v[68:69], v[72:73]
	v_pk_add_f32 v[64:65], v[66:67], v[64:65]
	s_nop 0
	v_pk_add_f32 v[64:65], v[64:65], v[68:69]
	s_nop 0
	v_add_f32_e32 v64, v64, v65
	s_nop 1
	v_add_f32_dpp v64, v64, v64 quad_perm:[1,0,3,2] row_mask:0xf bank_mask:0xf bound_ctrl:1
	s_nop 1
	v_add_f32_dpp v64, v64, v64 quad_perm:[2,3,0,1] row_mask:0xf bank_mask:0xf bound_ctrl:1
	s_nop 1
	v_add_f32_dpp v64, v64, v64 row_half_mirror row_mask:0xf bank_mask:0xf bound_ctrl:1
	s_nop 1
	v_add_f32_dpp v64, v64, v64 row_mirror row_mask:0xf bank_mask:0xf bound_ctrl:1
	s_nop 1
	v_mov_b32_dpp v45, v64 row_bcast:15 row_mask:0xa bank_mask:0xf
	v_add_f32_e32 v45, v64, v45
	s_nop 1
	v_mov_b32_dpp v75, v45 row_bcast:31 row_mask:0xc bank_mask:0xf
	v_add_f32_e32 v45, v45, v75
	s_nop 0
	v_readlane_b32 s0, v45, 63
	s_nop 1
	v_fma_f32 v45, s0, v44, v43
	v_mul_f32_e32 v64, 0x4b800000, v45
	v_cmp_gt_f32_e32 vcc, s11, v45
	s_nop 1
	v_cndmask_b32_e32 v45, v45, v64, vcc
	v_rsq_f32_e32 v45, v45
	s_nop 0
	v_mul_f32_e32 v64, 0x45800000, v45
	v_cndmask_b32_e32 v64, v45, v64, vcc
	v_pk_mul_f32 v[116:117], v[116:117], v[64:65] op_sel_hi:[1,0]
	v_pk_mul_f32 v[118:119], v[118:119], v[64:65] op_sel_hi:[1,0]
	v_pk_fma_f32 v[116:117], v[26:27], v[116:117], v[0:1]
	v_pk_mul_f32 v[120:121], v[120:121], v[64:65] op_sel_hi:[1,0]
	v_pk_mul_f32 v[122:123], v[122:123], v[64:65] op_sel_hi:[1,0]
	v_pk_fma_f32 v[118:119], v[24:25], v[118:119], v[2:3]
	v_cvt_pk_bf16_f32 v116, v116, v117
	v_pk_mul_f32 v[124:125], v[124:125], v[64:65] op_sel_hi:[1,0]
	v_cvt_pk_bf16_f32 v117, v118, v119
	v_pk_mul_f32 v[126:127], v[126:127], v[64:65] op_sel_hi:[1,0]
	v_pk_fma_f32 v[122:123], v[28:29], v[122:123], v[6:7]
	v_pk_fma_f32 v[120:121], v[30:31], v[120:121], v[4:5]
	global_store_dwordx2 v[62:63], v[116:117], off
	v_cvt_pk_bf16_f32 v116, v120, v121
	v_cvt_pk_bf16_f32 v117, v122, v123
	v_pk_mul_f32 v[128:129], v[128:129], v[64:65] op_sel_hi:[1,0]
	v_pk_mul_f32 v[130:131], v[130:131], v[64:65] op_sel_hi:[1,0]
	v_pk_fma_f32 v[126:127], v[32:33], v[126:127], v[10:11]
	v_pk_fma_f32 v[124:125], v[34:35], v[124:125], v[8:9]
	global_store_dwordx2 v[62:63], v[116:117], off offset:512
	v_cvt_pk_bf16_f32 v116, v124, v125
	v_cvt_pk_bf16_f32 v117, v126, v127
	v_pk_fma_f32 v[130:131], v[36:37], v[130:131], v[14:15]
	v_pk_fma_f32 v[128:129], v[38:39], v[128:129], v[12:13]
	global_store_dwordx2 v[62:63], v[116:117], off offset:1024
	v_cvt_pk_bf16_f32 v116, v128, v129
	v_cvt_pk_bf16_f32 v117, v130, v131
	global_store_dwordx2 v[62:63], v[116:117], off offset:1536
	s_cbranch_scc0 .LBB0_71
	s_add_i32 s12, s12, s87
	s_add_i32 s3, s3, s10
	s_cmpk_gt_i32 s12, 0x17ff
	s_cbranch_scc0 .LBB0_70

; __device__ __forceinline__ unsigned cvtpk(float lo, float hi) { unsigned r; asm volatile("v_cvt_pk_bf16_f32 %0, %1, %2" : "=v"(r) : "v"(lo), "v"(hi)); return r; }
; __device__ __forceinline__ void modnorm_phase(const Ctx& X, const float* src_p, const float* src_s, const float* g, const float* mod, int sh_off, int sc_off, bf16_t* H) {
;     ...
;         for (int r = 0; r < 16; ++r) {
;             const float* xr = src + (size_t)(t0 + r) * DM + X.lane * 4;
;             f32x4 v[4]; float ss = 0.f;
; #pragma unroll
;             for (int j = 0; j < 4; ++j) { v[j] = *(const f32x4*)(xr + 256 * j); ss += (v[j].x * v[j].x + v[j].y * v[j].y) + (v[j].z * v[j].z + v[j].w * v[j].w); }
;             const float rstd = rsqrtf(wave_sum(ss) * (1.f / DM) + EPS);
;             bf16_t* orow = H + (size_t)(t0 + r) * DM + X.lane * 4;
; #pragma unroll
;             for (int j = 0; j < 4; ++j) { const f32x4 o = v[j] * rstd * gs[j] + sh[j]; u32x2 w; w.x = cvtpk(o.x, o.y); w.y = cvtpk(o.z, o.w); *(u32x2*)(orow + 256 * j) = w; }
.LBB0_605:
	s_add_i32 s6, s3, s11
	s_ashr_i32 s7, s6, 31
	s_lshl_b64 s[12:13], s[6:7], 12
	v_lshl_add_u64 v[60:61], v[18:19], 0, s[12:13]
	global_load_dwordx4 v[44:47], v[60:61], off
	global_load_dwordx4 v[48:51], v[60:61], off offset:1024
	global_load_dwordx4 v[52:55], v[60:61], off offset:3072
	global_load_dwordx4 v[56:59], v[60:61], off offset:2048
	v_mov_b32_e32 v75, 0
	v_mov_b32_e32 v78, 0
	s_add_i32 s0, s6, 1
	s_lshl_b64 s[6:7], s[6:7], 11
	s_ashr_i32 s1, s0, 31
	v_lshl_add_u64 v[62:63], v[20:21], 0, s[6:7]
	s_lshl_b64 s[6:7], s[0:1], 12
	v_lshl_add_u64 v[60:61], v[18:19], 0, s[6:7]
	s_lshl_b64 s[0:1], s[0:1], 11
	global_load_dwordx4 v[84:87], v[60:61], off
	global_load_dwordx4 v[88:91], v[60:61], off offset:1024
	global_load_dwordx4 v[92:95], v[60:61], off offset:2048
	global_load_dwordx4 v[96:99], v[60:61], off offset:3072
	s_add_i32 s98, s3, s11
	s_add_i32 s98, s98, 2
	s_mov_b32 s99, 0
	s_lshl_b64 s[98:99], s[98:99], 12
	v_lshl_add_u64 v[132:133], v[18:19], 0, s[98:99]
	s_nop 0
	v_add_co_u32_e32 v134, vcc, 0x1000, v132
	s_nop 1
	v_addc_co_u32_e32 v135, vcc, 0, v133, vcc
	global_load_dwordx4 v[100:103], v[132:133], off
	global_load_dwordx4 v[104:107], v[132:133], off offset:1024
	global_load_dwordx4 v[108:111], v[132:133], off offset:3072
	global_load_dwordx4 v[112:115], v[132:133], off offset:2048
	global_load_dwordx4 v[116:119], v[134:135], off
	global_load_dwordx4 v[120:123], v[134:135], off offset:1024
	global_load_dwordx4 v[124:127], v[134:135], off offset:2048
	global_load_dwordx4 v[128:131], v[134:135], off offset:3072
	s_add_i32 s11, s11, 2
	s_cmp_eq_u32 s11, 16
	s_waitcnt vmcnt(15)
	v_pk_mul_f32 v[64:65], v[46:47], v[46:47]
	v_pk_mul_f32 v[66:67], v[44:45], v[44:45]
	s_waitcnt vmcnt(14)
	v_pk_mul_f32 v[68:69], v[50:51], v[50:51]
	v_pk_mul_f32 v[70:71], v[48:49], v[48:49]
	v_pk_mov_b32 v[76:77], v[66:67], v[64:65] op_sel:[1,0]
	v_mov_b32_e32 v67, v65
	v_pk_mov_b32 v[64:65], v[70:71], v[68:69] op_sel:[1,0]
	v_mov_b32_e32 v71, v69
	s_waitcnt vmcnt(12)
	v_mul_f32_e32 v72, v57, v57
	v_mul_f32_e32 v74, v59, v59
	v_pk_add_f32 v[66:67], v[76:77], v[66:67]
	v_pk_add_f32 v[64:65], v[64:65], v[70:71]
	v_mul_f32_e32 v79, v52, v52
	v_mul_f32_e32 v80, v53, v53
	v_mul_f32_e32 v81, v54, v54
	v_mul_f32_e32 v82, v55, v55
	v_pk_fma_f32 v[68:69], v[56:57], v[56:57], v[72:73] op_sel_hi:[1,1,0]
	v_pk_fma_f32 v[72:73], v[58:59], v[58:59], v[74:75] op_sel_hi:[1,1,0]
	v_pk_add_f32 v[66:67], v[66:67], v[66:67] op_sel:[0,1] op_sel_hi:[1,0]
	v_pk_add_f32 v[64:65], v[64:65], v[64:65] op_sel:[0,1] op_sel_hi:[1,0]
	v_mov_b32_e32 v69, v81
	v_mov_b32_e32 v73, v82
	v_mov_b32_e32 v67, v79
	v_mov_b32_e32 v65, v80
	v_pk_add_f32 v[68:69], v[68:69], v[72:73]
	v_pk_add_f32 v[64:65], v[66:67], v[64:65]
	v_mov_b32_e32 v73, 0
	v_pk_add_f32 v[64:65], v[64:65], v[68:69]
	v_mov_b32_e32 v76, 0
	v_add_f32_e32 v64, v64, v65
	s_nop 1
	v_add_f32_dpp v64, v64, v64 quad_perm:[1,0,3,2] row_mask:0xf bank_mask:0xf bound_ctrl:1
	s_nop 1
	v_add_f32_dpp v64, v64, v64 quad_perm:[2,3,0,1] row_mask:0xf bank_mask:0xf bound_ctrl:1
	s_nop 1
	v_add_f32_dpp v64, v64, v64 row_half_mirror row_mask:0xf bank_mask:0xf bound_ctrl:1
	s_nop 1
	v_add_f32_dpp v64, v64, v64 row_mirror row_mask:0xf bank_mask:0xf bound_ctrl:1
	s_nop 1
	v_mov_b32_dpp v75, v64 row_bcast:15 row_mask:0xa bank_mask:0xf
	v_add_f32_e32 v64, v64, v75
	s_nop 1
	v_mov_b32_dpp v78, v64 row_bcast:31 row_mask:0xc bank_mask:0xf
	v_add_f32_e32 v64, v64, v78
	s_nop 0
	v_readlane_b32 s6, v64, 63
	s_nop 1
	v_fma_f32 v64, s6, v43, v42
	v_mul_f32_e32 v65, 0x4b800000, v64
	v_cmp_gt_f32_e32 vcc, s9, v64
	s_nop 1
	v_cndmask_b32_e32 v64, v64, v65, vcc
	v_rsq_f32_e32 v64, v64
	s_nop 0
	v_mul_f32_e32 v65, 0x45800000, v64
	v_cndmask_b32_e32 v64, v64, v65, vcc
	v_pk_mul_f32 v[44:45], v[44:45], v[64:65] op_sel_hi:[1,0]
	v_pk_mul_f32 v[46:47], v[46:47], v[64:65] op_sel_hi:[1,0]
	v_pk_fma_f32 v[44:45], v[24:25], v[44:45], v[0:1]
	v_pk_mul_f32 v[48:49], v[48:49], v[64:65] op_sel_hi:[1,0]
	v_pk_mul_f32 v[50:51], v[50:51], v[64:65] op_sel_hi:[1,0]
	v_pk_fma_f32 v[46:47], v[22:23], v[46:47], v[2:3]
	v_cvt_pk_bf16_f32 v44, v44, v45
	v_pk_mul_f32 v[56:57], v[56:57], v[64:65] op_sel_hi:[1,0]
	v_cvt_pk_bf16_f32 v45, v46, v47
	v_pk_mul_f32 v[58:59], v[58:59], v[64:65] op_sel_hi:[1,0]
	v_pk_fma_f32 v[50:51], v[26:27], v[50:51], v[6:7]
	v_pk_fma_f32 v[48:49], v[28:29], v[48:49], v[4:5]
	global_store_dwordx2 v[62:63], v[44:45], off
	v_cvt_pk_bf16_f32 v44, v48, v49
	v_cvt_pk_bf16_f32 v45, v50, v51
	v_pk_mul_f32 v[52:53], v[52:53], v[64:65] op_sel_hi:[1,0]
	v_pk_mul_f32 v[54:55], v[54:55], v[64:65] op_sel_hi:[1,0]
	v_pk_fma_f32 v[58:59], v[30:31], v[58:59], v[10:11]
	v_pk_fma_f32 v[56:57], v[32:33], v[56:57], v[8:9]
	global_store_dwordx2 v[62:63], v[44:45], off offset:512
	v_cvt_pk_bf16_f32 v44, v56, v57
	v_cvt_pk_bf16_f32 v45, v58, v59
	v_pk_fma_f32 v[54:55], v[34:35], v[54:55], v[14:15]
	v_pk_fma_f32 v[52:53], v[36:37], v[52:53], v[12:13]
	global_store_dwordx2 v[62:63], v[44:45], off offset:1024
	v_cvt_pk_bf16_f32 v44, v52, v53
	v_cvt_pk_bf16_f32 v45, v54, v55
	global_store_dwordx2 v[62:63], v[44:45], off offset:1536
	v_lshl_add_u64 v[60:61], v[20:21], 0, s[0:1]
	s_waitcnt vmcnt(15)
	v_pk_mul_f32 v[62:63], v[86:87], v[86:87]
	v_pk_mul_f32 v[64:65], v[84:85], v[84:85]
	s_waitcnt vmcnt(14)
	v_pk_mul_f32 v[66:67], v[90:91], v[90:91]
	v_pk_mul_f32 v[68:69], v[88:89], v[88:89]
	v_pk_mov_b32 v[74:75], v[64:65], v[62:63] op_sel:[1,0]
	v_mov_b32_e32 v65, v63
	v_pk_mov_b32 v[62:63], v[68:69], v[66:67] op_sel:[1,0]
	v_mov_b32_e32 v69, v67
	s_waitcnt vmcnt(13)
	v_mul_f32_e32 v70, v93, v93
	v_mul_f32_e32 v72, v95, v95
	v_pk_add_f32 v[64:65], v[74:75], v[64:65]
	v_pk_add_f32 v[62:63], v[62:63], v[68:69]
	s_waitcnt vmcnt(12)
; __device__ __forceinline__ unsigned cvtpk(float lo, float hi) { unsigned r; asm volatile("v_cvt_pk_bf16_f32 %0, %1, %2" : "=v"(r) : "v"(lo), "v"(hi)); return r; }
; __device__ __forceinline__ void modnorm_phase(const Ctx& X, const float* src_p, const float* src_s, const float* g, const float* mod, int sh_off, int sc_off, bf16_t* H) {
;     ...
;         for (int r = 0; r < 16; ++r) {
;             const float* xr = src + (size_t)(t0 + r) * DM + X.lane * 4;
;             f32x4 v[4]; float ss = 0.f;
; #pragma unroll
;             for (int j = 0; j < 4; ++j) { v[j] = *(const f32x4*)(xr + 256 * j); ss += (v[j].x * v[j].x + v[j].y * v[j].y) + (v[j].z * v[j].z + v[j].w * v[j].w); }
;             const float rstd = rsqrtf(wave_sum(ss) * (1.f / DM) + EPS);
;             bf16_t* orow = H + (size_t)(t0 + r) * DM + X.lane * 4;
; #pragma unroll
;             for (int j = 0; j < 4; ++j) { const f32x4 o = v[j] * rstd * gs[j] + sh[j]; u32x2 w; w.x = cvtpk(o.x, o.y); w.y = cvtpk(o.z, o.w); *(u32x2*)(orow + 256 * j) = w; }
;         }
	v_mul_f32_e32 v77, v96, v96
	v_mul_f32_e32 v78, v97, v97
	v_mul_f32_e32 v79, v98, v98
	v_mul_f32_e32 v80, v99, v99
	v_pk_fma_f32 v[66:67], v[92:93], v[92:93], v[70:71] op_sel_hi:[1,1,0]
	v_pk_fma_f32 v[70:71], v[94:95], v[94:95], v[72:73] op_sel_hi:[1,1,0]
	v_pk_add_f32 v[64:65], v[64:65], v[64:65] op_sel:[0,1] op_sel_hi:[1,0]
	v_pk_add_f32 v[62:63], v[62:63], v[62:63] op_sel:[0,1] op_sel_hi:[1,0]
	v_mov_b32_e32 v67, v79
	v_mov_b32_e32 v71, v80
	v_mov_b32_e32 v65, v77
	v_mov_b32_e32 v63, v78
	v_pk_add_f32 v[66:67], v[66:67], v[70:71]
	v_pk_add_f32 v[62:63], v[64:65], v[62:63]
	s_nop 0
	v_pk_add_f32 v[62:63], v[62:63], v[66:67]
	s_nop 0
	v_add_f32_e32 v62, v62, v63
	s_nop 1
	v_add_f32_dpp v62, v62, v62 quad_perm:[1,0,3,2] row_mask:0xf bank_mask:0xf bound_ctrl:1
	s_nop 1
	v_add_f32_dpp v62, v62, v62 quad_perm:[2,3,0,1] row_mask:0xf bank_mask:0xf bound_ctrl:1
	s_nop 1
	v_add_f32_dpp v62, v62, v62 row_half_mirror row_mask:0xf bank_mask:0xf bound_ctrl:1
	s_nop 1
	v_add_f32_dpp v62, v62, v62 row_mirror row_mask:0xf bank_mask:0xf bound_ctrl:1
	s_nop 1
	v_mov_b32_dpp v73, v62 row_bcast:15 row_mask:0xa bank_mask:0xf
	v_add_f32_e32 v62, v62, v73
	s_nop 1
	v_mov_b32_dpp v76, v62 row_bcast:31 row_mask:0xc bank_mask:0xf
	v_add_f32_e32 v62, v62, v76
	s_nop 0
	v_readlane_b32 s0, v62, 63
	s_nop 1
	v_fma_f32 v62, s0, v43, v42
	v_mul_f32_e32 v63, 0x4b800000, v62
	v_cmp_gt_f32_e32 vcc, s9, v62
	s_nop 1
	v_cndmask_b32_e32 v62, v62, v63, vcc
	v_rsq_f32_e32 v62, v62
	s_nop 0
	v_mul_f32_e32 v63, 0x45800000, v62
	v_cndmask_b32_e32 v62, v62, v63, vcc
	v_pk_mul_f32 v[84:85], v[84:85], v[62:63] op_sel_hi:[1,0]
	v_pk_mul_f32 v[86:87], v[86:87], v[62:63] op_sel_hi:[1,0]
	v_pk_fma_f32 v[84:85], v[24:25], v[84:85], v[0:1]
	v_pk_mul_f32 v[88:89], v[88:89], v[62:63] op_sel_hi:[1,0]
	v_pk_mul_f32 v[90:91], v[90:91], v[62:63] op_sel_hi:[1,0]
	v_pk_fma_f32 v[86:87], v[22:23], v[86:87], v[2:3]
	v_cvt_pk_bf16_f32 v84, v84, v85
	v_pk_mul_f32 v[92:93], v[92:93], v[62:63] op_sel_hi:[1,0]
	v_cvt_pk_bf16_f32 v85, v86, v87
	v_pk_mul_f32 v[94:95], v[94:95], v[62:63] op_sel_hi:[1,0]
	v_pk_fma_f32 v[90:91], v[26:27], v[90:91], v[6:7]
	v_pk_fma_f32 v[88:89], v[28:29], v[88:89], v[4:5]
	global_store_dwordx2 v[60:61], v[84:85], off
	v_cvt_pk_bf16_f32 v84, v88, v89
	v_cvt_pk_bf16_f32 v85, v90, v91
	v_pk_mul_f32 v[96:97], v[96:97], v[62:63] op_sel_hi:[1,0]
	v_pk_mul_f32 v[98:99], v[98:99], v[62:63] op_sel_hi:[1,0]
	v_pk_fma_f32 v[94:95], v[30:31], v[94:95], v[10:11]
	v_pk_fma_f32 v[92:93], v[32:33], v[92:93], v[8:9]
	global_store_dwordx2 v[60:61], v[84:85], off offset:512
	v_cvt_pk_bf16_f32 v84, v92, v93
	v_cvt_pk_bf16_f32 v85, v94, v95
	v_pk_fma_f32 v[98:99], v[34:35], v[98:99], v[14:15]
	v_pk_fma_f32 v[96:97], v[36:37], v[96:97], v[12:13]
	global_store_dwordx2 v[60:61], v[84:85], off offset:1024
	v_cvt_pk_bf16_f32 v84, v96, v97
	v_cvt_pk_bf16_f32 v85, v98, v99
	global_store_dwordx2 v[60:61], v[84:85], off offset:1536
	s_add_i32 s6, s3, s11
	s_ashr_i32 s7, s6, 31
	s_lshl_b64 s[12:13], s[6:7], 12
	v_lshl_add_u64 v[60:61], v[18:19], 0, s[12:13]
	v_mov_b32_e32 v75, 0
	v_mov_b32_e32 v78, 0
	s_add_i32 s0, s6, 1
	s_lshl_b64 s[6:7], s[6:7], 11
	s_ashr_i32 s1, s0, 31
	v_lshl_add_u64 v[62:63], v[20:21], 0, s[6:7]
	s_lshl_b64 s[6:7], s[0:1], 12
	v_lshl_add_u64 v[60:61], v[18:19], 0, s[6:7]
	s_lshl_b64 s[0:1], s[0:1], 11
	s_add_i32 s11, s11, 2
	s_cmp_eq_u32 s11, 16
	s_waitcnt vmcnt(15)
	v_pk_mul_f32 v[64:65], v[102:103], v[102:103]
	v_pk_mul_f32 v[66:67], v[100:101], v[100:101]
	s_waitcnt vmcnt(14)
	v_pk_mul_f32 v[68:69], v[106:107], v[106:107]
	v_pk_mul_f32 v[70:71], v[104:105], v[104:105]
	v_pk_mov_b32 v[76:77], v[66:67], v[64:65] op_sel:[1,0]
	v_mov_b32_e32 v67, v65
	v_pk_mov_b32 v[64:65], v[70:71], v[68:69] op_sel:[1,0]
	v_mov_b32_e32 v71, v69
	s_waitcnt vmcnt(12)
; __device__ __forceinline__ unsigned cvtpk(float lo, float hi) { unsigned r; asm volatile("v_cvt_pk_bf16_f32 %0, %1, %2" : "=v"(r) : "v"(lo), "v"(hi)); return r; }
; #define WS_DPP(x, ctrl, rmask) __builtin_bit_cast(float, __builtin_amdgcn_update_dpp(0, __builtin_bit_cast(int, (x)), (ctrl), (rmask), 0xf, false))
; __device__ __forceinline__ float wave_sum(float v) {
;     ...
;     v += WS_DPP(v, 0xB1, 0xf);
;     v += WS_DPP(v, 0x4E, 0xf);
;     v += WS_DPP(v, 0x141, 0xf);
;     v += WS_DPP(v, 0x140, 0xf);
;     v += WS_DPP(v, 0x142, 0xa);
;     v += WS_DPP(v, 0x143, 0xc);
;     ...
;     return __builtin_bit_cast(float, __builtin_amdgcn_readlane(__builtin_bit_cast(int, v), 63));
; }
; __device__ __forceinline__ void modnorm_phase(const Ctx& X, const float* src_p, const float* src_s, const float* g, const float* mod, int sh_off, int sc_off, bf16_t* H) {
;     ...
;         for (int r = 0; r < 16; ++r) {
;             const float* xr = src + (size_t)(t0 + r) * DM + X.lane * 4;
;             f32x4 v[4]; float ss = 0.f;
; #pragma unroll
;             for (int j = 0; j < 4; ++j) { v[j] = *(const f32x4*)(xr + 256 * j); ss += (v[j].x * v[j].x + v[j].y * v[j].y) + (v[j].z * v[j].z + v[j].w * v[j].w); }
;             const float rstd = rsqrtf(wave_sum(ss) * (1.f / DM) + EPS);
;             bf16_t* orow = H + (size_t)(t0 + r) * DM + X.lane * 4;
; #pragma unroll
;             for (int j = 0; j < 4; ++j) { const f32x4 o = v[j] * rstd * gs[j] + sh[j]; u32x2 w; w.x = cvtpk(o.x, o.y); w.y = cvtpk(o.z, o.w); *(u32x2*)(orow + 256 * j) = w; }
;         }
	v_mul_f32_e32 v72, v113, v113
	v_mul_f32_e32 v74, v115, v115
	v_pk_add_f32 v[66:67], v[76:77], v[66:67]
	v_pk_add_f32 v[64:65], v[64:65], v[70:71]
	v_mul_f32_e32 v79, v108, v108
	v_mul_f32_e32 v80, v109, v109
	v_mul_f32_e32 v81, v110, v110
	v_mul_f32_e32 v82, v111, v111
	v_pk_fma_f32 v[68:69], v[112:113], v[112:113], v[72:73] op_sel_hi:[1,1,0]
	v_pk_fma_f32 v[72:73], v[114:115], v[114:115], v[74:75] op_sel_hi:[1,1,0]
	v_pk_add_f32 v[66:67], v[66:67], v[66:67] op_sel:[0,1] op_sel_hi:[1,0]
	v_pk_add_f32 v[64:65], v[64:65], v[64:65] op_sel:[0,1] op_sel_hi:[1,0]
	v_mov_b32_e32 v69, v81
	v_mov_b32_e32 v73, v82
	v_mov_b32_e32 v67, v79
	v_mov_b32_e32 v65, v80
	v_pk_add_f32 v[68:69], v[68:69], v[72:73]
	v_pk_add_f32 v[64:65], v[66:67], v[64:65]
	v_mov_b32_e32 v73, 0
	v_pk_add_f32 v[64:65], v[64:65], v[68:69]
	v_mov_b32_e32 v76, 0
	v_add_f32_e32 v64, v64, v65
	s_nop 1
	v_add_f32_dpp v64, v64, v64 quad_perm:[1,0,3,2] row_mask:0xf bank_mask:0xf bound_ctrl:1
	s_nop 1
	v_add_f32_dpp v64, v64, v64 quad_perm:[2,3,0,1] row_mask:0xf bank_mask:0xf bound_ctrl:1
	s_nop 1
	v_add_f32_dpp v64, v64, v64 row_half_mirror row_mask:0xf bank_mask:0xf bound_ctrl:1
	s_nop 1
	v_add_f32_dpp v64, v64, v64 row_mirror row_mask:0xf bank_mask:0xf bound_ctrl:1
	s_nop 1
	v_mov_b32_dpp v75, v64 row_bcast:15 row_mask:0xa bank_mask:0xf
	v_add_f32_e32 v64, v64, v75
	s_nop 1
	v_mov_b32_dpp v78, v64 row_bcast:31 row_mask:0xc bank_mask:0xf
	v_add_f32_e32 v64, v64, v78
	s_nop 0
	v_readlane_b32 s6, v64, 63
	s_nop 1
	v_fma_f32 v64, s6, v43, v42
	v_mul_f32_e32 v65, 0x4b800000, v64
	v_cmp_gt_f32_e32 vcc, s9, v64
	s_nop 1
	v_cndmask_b32_e32 v64, v64, v65, vcc
	v_rsq_f32_e32 v64, v64
	s_nop 0
	v_mul_f32_e32 v65, 0x45800000, v64
	v_cndmask_b32_e32 v64, v64, v65, vcc
	v_pk_mul_f32 v[100:101], v[100:101], v[64:65] op_sel_hi:[1,0]
	v_pk_mul_f32 v[102:103], v[102:103], v[64:65] op_sel_hi:[1,0]
	v_pk_fma_f32 v[100:101], v[24:25], v[100:101], v[0:1]
	v_pk_mul_f32 v[104:105], v[104:105], v[64:65] op_sel_hi:[1,0]
	v_pk_mul_f32 v[106:107], v[106:107], v[64:65] op_sel_hi:[1,0]
	v_pk_fma_f32 v[102:103], v[22:23], v[102:103], v[2:3]
	v_cvt_pk_bf16_f32 v100, v100, v101
	v_pk_mul_f32 v[112:113], v[112:113], v[64:65] op_sel_hi:[1,0]
	v_cvt_pk_bf16_f32 v101, v102, v103
	v_pk_mul_f32 v[114:115], v[114:115], v[64:65] op_sel_hi:[1,0]
	v_pk_fma_f32 v[106:107], v[26:27], v[106:107], v[6:7]
	v_pk_fma_f32 v[104:105], v[28:29], v[104:105], v[4:5]
	global_store_dwordx2 v[62:63], v[100:101], off
	v_cvt_pk_bf16_f32 v100, v104, v105
	v_cvt_pk_bf16_f32 v101, v106, v107
	v_pk_mul_f32 v[108:109], v[108:109], v[64:65] op_sel_hi:[1,0]
	v_pk_mul_f32 v[110:111], v[110:111], v[64:65] op_sel_hi:[1,0]
	v_pk_fma_f32 v[114:115], v[30:31], v[114:115], v[10:11]
	v_pk_fma_f32 v[112:113], v[32:33], v[112:113], v[8:9]
	global_store_dwordx2 v[62:63], v[100:101], off offset:512
	v_cvt_pk_bf16_f32 v100, v112, v113
	v_cvt_pk_bf16_f32 v101, v114, v115
	v_pk_fma_f32 v[110:111], v[34:35], v[110:111], v[14:15]
	v_pk_fma_f32 v[108:109], v[36:37], v[108:109], v[12:13]
	global_store_dwordx2 v[62:63], v[100:101], off offset:1024
	v_cvt_pk_bf16_f32 v100, v108, v109
	v_cvt_pk_bf16_f32 v101, v110, v111
	global_store_dwordx2 v[62:63], v[100:101], off offset:1536
	v_lshl_add_u64 v[60:61], v[20:21], 0, s[0:1]
	s_waitcnt vmcnt(15)
	v_pk_mul_f32 v[62:63], v[118:119], v[118:119]
	v_pk_mul_f32 v[64:65], v[116:117], v[116:117]
	s_waitcnt vmcnt(14)
	v_pk_mul_f32 v[66:67], v[122:123], v[122:123]
	v_pk_mul_f32 v[68:69], v[120:121], v[120:121]
	v_pk_mov_b32 v[74:75], v[64:65], v[62:63] op_sel:[1,0]
	v_mov_b32_e32 v65, v63
	v_pk_mov_b32 v[62:63], v[68:69], v[66:67] op_sel:[1,0]
	v_mov_b32_e32 v69, v67
	s_waitcnt vmcnt(13)
	v_mul_f32_e32 v70, v125, v125
	v_mul_f32_e32 v72, v127, v127
	v_pk_add_f32 v[64:65], v[74:75], v[64:65]
	v_pk_add_f32 v[62:63], v[62:63], v[68:69]
	s_waitcnt vmcnt(12)
	v_mul_f32_e32 v77, v128, v128
	v_mul_f32_e32 v78, v129, v129
	v_mul_f32_e32 v79, v130, v130
	v_mul_f32_e32 v80, v131, v131
	v_pk_fma_f32 v[66:67], v[124:125], v[124:125], v[70:71] op_sel_hi:[1,1,0]
	v_pk_fma_f32 v[70:71], v[126:127], v[126:127], v[72:73] op_sel_hi:[1,1,0]
	v_pk_add_f32 v[64:65], v[64:65], v[64:65] op_sel:[0,1] op_sel_hi:[1,0]
	v_pk_add_f32 v[62:63], v[62:63], v[62:63] op_sel:[0,1] op_sel_hi:[1,0]
	v_mov_b32_e32 v67, v79
	v_mov_b32_e32 v71, v80
	v_mov_b32_e32 v65, v77
	v_mov_b32_e32 v63, v78
	v_pk_add_f32 v[66:67], v[66:67], v[70:71]
	v_pk_add_f32 v[62:63], v[64:65], v[62:63]
	s_nop 0
	v_pk_add_f32 v[62:63], v[62:63], v[66:67]
	s_nop 0
	v_add_f32_e32 v62, v62, v63
	s_nop 1
	v_add_f32_dpp v62, v62, v62 quad_perm:[1,0,3,2] row_mask:0xf bank_mask:0xf bound_ctrl:1
	s_nop 1
	v_add_f32_dpp v62, v62, v62 quad_perm:[2,3,0,1] row_mask:0xf bank_mask:0xf bound_ctrl:1
	s_nop 1
	v_add_f32_dpp v62, v62, v62 row_half_mirror row_mask:0xf bank_mask:0xf bound_ctrl:1
	s_nop 1
	v_add_f32_dpp v62, v62, v62 row_mirror row_mask:0xf bank_mask:0xf bound_ctrl:1
	s_nop 1
	v_mov_b32_dpp v73, v62 row_bcast:15 row_mask:0xa bank_mask:0xf
	v_add_f32_e32 v62, v62, v73
	s_nop 1
	v_mov_b32_dpp v76, v62 row_bcast:31 row_mask:0xc bank_mask:0xf
	v_add_f32_e32 v62, v62, v76
	s_nop 0
	v_readlane_b32 s0, v62, 63
	s_nop 1
	v_fma_f32 v62, s0, v43, v42
	v_mul_f32_e32 v63, 0x4b800000, v62
	v_cmp_gt_f32_e32 vcc, s9, v62
	s_nop 1
	v_cndmask_b32_e32 v62, v62, v63, vcc
	v_rsq_f32_e32 v62, v62
	s_nop 0
	v_mul_f32_e32 v63, 0x45800000, v62
	v_cndmask_b32_e32 v62, v62, v63, vcc
	v_pk_mul_f32 v[116:117], v[116:117], v[62:63] op_sel_hi:[1,0]
	v_pk_mul_f32 v[118:119], v[118:119], v[62:63] op_sel_hi:[1,0]
	v_pk_fma_f32 v[116:117], v[24:25], v[116:117], v[0:1]
	v_pk_mul_f32 v[120:121], v[120:121], v[62:63] op_sel_hi:[1,0]
	v_pk_mul_f32 v[122:123], v[122:123], v[62:63] op_sel_hi:[1,0]
	v_pk_fma_f32 v[118:119], v[22:23], v[118:119], v[2:3]
	v_cvt_pk_bf16_f32 v116, v116, v117
	v_pk_mul_f32 v[124:125], v[124:125], v[62:63] op_sel_hi:[1,0]
	v_cvt_pk_bf16_f32 v117, v118, v119
	v_pk_mul_f32 v[126:127], v[126:127], v[62:63] op_sel_hi:[1,0]
	v_pk_fma_f32 v[122:123], v[26:27], v[122:123], v[6:7]
	v_pk_fma_f32 v[120:121], v[28:29], v[120:121], v[4:5]
	global_store_dwordx2 v[60:61], v[116:117], off
	v_cvt_pk_bf16_f32 v116, v120, v121
	v_cvt_pk_bf16_f32 v117, v122, v123
	v_pk_mul_f32 v[128:129], v[128:129], v[62:63] op_sel_hi:[1,0]
	v_pk_mul_f32 v[130:131], v[130:131], v[62:63] op_sel_hi:[1,0]
	v_pk_fma_f32 v[126:127], v[30:31], v[126:127], v[10:11]
	v_pk_fma_f32 v[124:125], v[32:33], v[124:125], v[8:9]
	global_store_dwordx2 v[60:61], v[116:117], off offset:512
	v_cvt_pk_bf16_f32 v116, v124, v125
	v_cvt_pk_bf16_f32 v117, v126, v127
	v_pk_fma_f32 v[130:131], v[34:35], v[130:131], v[14:15]
	v_pk_fma_f32 v[128:129], v[36:37], v[128:129], v[12:13]
	global_store_dwordx2 v[60:61], v[116:117], off offset:1024
	v_cvt_pk_bf16_f32 v116, v128, v129
	v_cvt_pk_bf16_f32 v117, v130, v131
	global_store_dwordx2 v[60:61], v[116:117], off offset:1536
	s_cbranch_scc0 .LBB0_605
	s_add_i32 s10, s10, s87
	s_add_i32 s3, s3, s8
	s_cmpk_gt_i32 s10, 0x17ff
	s_cbranch_scc0 .LBB0_604

; __device__ __forceinline__ void final_norm_phase(const Ctx& X, float* out, const float* g) {
;     ...
;     for (int ch = X.gw; ch < T_ALL / 16; ch += X.NGW) {
; #pragma unroll 2
;         for (int r = 0; r < 16; ++r) { float* xr = out + (size_t)(ch * 16 + r) * DM + X.lane * 4;
;             f32x4 v[4]; float ss = 0.f;
; #pragma unroll
;             for (int j = 0; j < 4; ++j) { v[j] = *(const f32x4*)(xr + 256 * j); ss += (v[j].x * v[j].x + v[j].y * v[j].y) + (v[j].z * v[j].z + v[j].w * v[j].w); }
;             const float rstd = rsqrtf(wave_sum(ss) * (1.f / DM) + EPS);
; #pragma unroll
;             for (int j = 0; j < 4; ++j) *(f32x4*)(xr + 256 * j) = v[j] * rstd * gv[j]; }
.LBB0_885:
	global_load_dwordx4 v[24:27], v[20:21], off offset:-2048
	global_load_dwordx4 v[28:31], v[20:21], off offset:-1024
	global_load_dwordx4 v[32:35], v[20:21], off offset:1024
	global_load_dwordx4 v[36:39], v[20:21], off
	v_mov_b32_e32 v53, 0
	v_mov_b32_e32 v56, 0
	s_add_i32 s8, s4, s1
	s_ashr_i32 s9, s8, 31
	s_lshl_b64 s[8:9], s[8:9], 12
	v_lshl_add_u64 v[40:41], v[16:17], 0, s[8:9]
	global_load_dwordx4 v[64:67], v[40:41], off
	global_load_dwordx4 v[68:71], v[40:41], off offset:1024
	global_load_dwordx4 v[72:75], v[40:41], off offset:2048
	global_load_dwordx4 v[76:79], v[40:41], off offset:3072
	v_lshl_add_u64 v[112:113], v[20:21], 0, s[2:3]
	v_lshl_add_u64 v[114:115], v[40:41], 0, s[2:3]
	global_load_dwordx4 v[80:83], v[112:113], off offset:-2048
	global_load_dwordx4 v[84:87], v[112:113], off offset:-1024
	global_load_dwordx4 v[88:91], v[112:113], off offset:1024
	global_load_dwordx4 v[92:95], v[112:113], off
	global_load_dwordx4 v[96:99], v[114:115], off
	global_load_dwordx4 v[100:103], v[114:115], off offset:1024
	global_load_dwordx4 v[104:107], v[114:115], off offset:2048
	global_load_dwordx4 v[108:111], v[114:115], off offset:3072
	s_add_i32 s1, s1, 2
	s_cmp_eq_u32 s1, 16
	s_waitcnt vmcnt(15)
	v_pk_mul_f32 v[42:43], v[26:27], v[26:27]
	v_pk_mul_f32 v[44:45], v[24:25], v[24:25]
	s_waitcnt vmcnt(14)
	v_pk_mul_f32 v[46:47], v[30:31], v[30:31]
	v_pk_mul_f32 v[48:49], v[28:29], v[28:29]
	v_pk_mov_b32 v[54:55], v[44:45], v[42:43] op_sel:[1,0]
	v_mov_b32_e32 v45, v43
	v_pk_mov_b32 v[42:43], v[48:49], v[46:47] op_sel:[1,0]
	v_mov_b32_e32 v49, v47
	s_waitcnt vmcnt(12)
	v_mul_f32_e32 v50, v37, v37
	v_mul_f32_e32 v52, v39, v39
	v_pk_add_f32 v[44:45], v[54:55], v[44:45]
	v_pk_add_f32 v[42:43], v[42:43], v[48:49]
	v_mul_f32_e32 v57, v32, v32
	v_mul_f32_e32 v58, v33, v33
	v_mul_f32_e32 v59, v34, v34
	v_mul_f32_e32 v60, v35, v35
	v_pk_fma_f32 v[46:47], v[36:37], v[36:37], v[50:51] op_sel_hi:[1,1,0]
	v_pk_fma_f32 v[50:51], v[38:39], v[38:39], v[52:53] op_sel_hi:[1,1,0]
	v_pk_add_f32 v[44:45], v[44:45], v[44:45] op_sel:[0,1] op_sel_hi:[1,0]
	v_pk_add_f32 v[42:43], v[42:43], v[42:43] op_sel:[0,1] op_sel_hi:[1,0]
	v_mov_b32_e32 v47, v59
	v_mov_b32_e32 v51, v60
	v_mov_b32_e32 v45, v57
	v_mov_b32_e32 v43, v58
	v_pk_add_f32 v[46:47], v[46:47], v[50:51]
	v_pk_add_f32 v[42:43], v[44:45], v[42:43]
	s_nop 0
	v_pk_add_f32 v[42:43], v[42:43], v[46:47]
	s_nop 0
	v_add_f32_e32 v42, v42, v43
	s_nop 1
	v_add_f32_dpp v42, v42, v42 quad_perm:[1,0,3,2] row_mask:0xf bank_mask:0xf bound_ctrl:1
	s_nop 1
	v_add_f32_dpp v42, v42, v42 quad_perm:[2,3,0,1] row_mask:0xf bank_mask:0xf bound_ctrl:1
	s_nop 1
	v_add_f32_dpp v42, v42, v42 row_half_mirror row_mask:0xf bank_mask:0xf bound_ctrl:1
	s_nop 1
	v_add_f32_dpp v42, v42, v42 row_mirror row_mask:0xf bank_mask:0xf bound_ctrl:1
	s_nop 1
	v_mov_b32_dpp v53, v42 row_bcast:15 row_mask:0xa bank_mask:0xf
	v_add_f32_e32 v42, v42, v53
	v_mov_b32_e32 v53, 0
	s_nop 0
	v_mov_b32_dpp v56, v42 row_bcast:31 row_mask:0xc bank_mask:0xf
	v_add_f32_e32 v42, v42, v56
	v_mov_b32_e32 v56, 0
	v_readlane_b32 s7, v42, 63
	s_nop 1
	v_fma_f32 v42, s7, v23, v22
	v_mul_f32_e32 v43, 0x4b800000, v42
	v_cmp_gt_f32_e32 vcc, s6, v42
	s_nop 1
	v_cndmask_b32_e32 v42, v42, v43, vcc
	v_rsq_f32_e32 v42, v42
	s_nop 0
	v_mul_f32_e32 v43, 0x45800000, v42
	v_cndmask_b32_e32 v42, v42, v43, vcc
	v_pk_mul_f32 v[24:25], v[24:25], v[42:43] op_sel_hi:[1,0]
	v_pk_mul_f32 v[26:27], v[26:27], v[42:43] op_sel_hi:[1,0]
	v_pk_mul_f32 v[28:29], v[28:29], v[42:43] op_sel_hi:[1,0]
	v_pk_mul_f32 v[30:31], v[30:31], v[42:43] op_sel_hi:[1,0]
	v_pk_mul_f32 v[36:37], v[36:37], v[42:43] op_sel_hi:[1,0]
	v_pk_mul_f32 v[38:39], v[38:39], v[42:43] op_sel_hi:[1,0]
	v_pk_mul_f32 v[44:45], v[32:33], v[42:43] op_sel_hi:[1,0]
	v_pk_mul_f32 v[42:43], v[34:35], v[42:43] op_sel_hi:[1,0]
	v_pk_mul_f32 v[26:27], v[2:3], v[26:27]
	v_pk_mul_f32 v[24:25], v[0:1], v[24:25]
	v_pk_mul_f32 v[30:31], v[6:7], v[30:31]
	v_pk_mul_f32 v[28:29], v[4:5], v[28:29]
	v_pk_mul_f32 v[34:35], v[10:11], v[38:39]
	v_pk_mul_f32 v[32:33], v[8:9], v[36:37]
	v_pk_mul_f32 v[38:39], v[14:15], v[42:43]
	v_pk_mul_f32 v[36:37], v[12:13], v[44:45]
	global_store_dwordx4 v[20:21], v[24:27], off offset:-2048
	global_store_dwordx4 v[20:21], v[28:31], off offset:-1024
	global_store_dwordx4 v[20:21], v[32:35], off
	global_store_dwordx4 v[20:21], v[36:39], off offset:1024
	v_lshl_add_u64 v[20:21], v[20:21], 0, s[2:3]
	s_waitcnt vmcnt(15)
	v_pk_mul_f32 v[42:43], v[66:67], v[66:67]
	v_pk_mul_f32 v[44:45], v[64:65], v[64:65]
	s_waitcnt vmcnt(14)
	v_pk_mul_f32 v[46:47], v[70:71], v[70:71]
	v_pk_mul_f32 v[48:49], v[68:69], v[68:69]
	v_pk_mov_b32 v[54:55], v[44:45], v[42:43] op_sel:[1,0]
	v_mov_b32_e32 v45, v43
	v_pk_mov_b32 v[42:43], v[48:49], v[46:47] op_sel:[1,0]
	v_mov_b32_e32 v49, v47
	s_waitcnt vmcnt(13)
	v_mul_f32_e32 v50, v73, v73
	v_mul_f32_e32 v52, v75, v75
	v_pk_add_f32 v[44:45], v[54:55], v[44:45]
	v_pk_add_f32 v[42:43], v[42:43], v[48:49]
	s_waitcnt vmcnt(12)
; __device__ __forceinline__ void final_norm_phase(const Ctx& X, float* out, const float* g) {
;     ...
;         for (int r = 0; r < 16; ++r) { float* xr = out + (size_t)(ch * 16 + r) * DM + X.lane * 4;
;             f32x4 v[4]; float ss = 0.f;
; #pragma unroll
;             for (int j = 0; j < 4; ++j) { v[j] = *(const f32x4*)(xr + 256 * j); ss += (v[j].x * v[j].x + v[j].y * v[j].y) + (v[j].z * v[j].z + v[j].w * v[j].w); }
;             const float rstd = rsqrtf(wave_sum(ss) * (1.f / DM) + EPS);
; #pragma unroll
;             for (int j = 0; j < 4; ++j) *(f32x4*)(xr + 256 * j) = v[j] * rstd * gv[j]; }
	v_mul_f32_e32 v57, v76, v76
	v_mul_f32_e32 v58, v77, v77
	v_mul_f32_e32 v59, v78, v78
	v_mul_f32_e32 v60, v79, v79
	v_pk_fma_f32 v[46:47], v[72:73], v[72:73], v[50:51] op_sel_hi:[1,1,0]
	v_pk_fma_f32 v[50:51], v[74:75], v[74:75], v[52:53] op_sel_hi:[1,1,0]
	v_pk_add_f32 v[44:45], v[44:45], v[44:45] op_sel:[0,1] op_sel_hi:[1,0]
	v_pk_add_f32 v[42:43], v[42:43], v[42:43] op_sel:[0,1] op_sel_hi:[1,0]
	v_mov_b32_e32 v47, v59
	v_mov_b32_e32 v51, v60
	v_mov_b32_e32 v45, v57
	v_mov_b32_e32 v43, v58
	v_pk_add_f32 v[46:47], v[46:47], v[50:51]
	v_pk_add_f32 v[42:43], v[44:45], v[42:43]
	s_nop 0
	v_pk_add_f32 v[42:43], v[42:43], v[46:47]
	s_nop 0
	v_add_f32_e32 v42, v42, v43
	s_nop 1
	v_add_f32_dpp v42, v42, v42 quad_perm:[1,0,3,2] row_mask:0xf bank_mask:0xf bound_ctrl:1
	s_nop 1
	v_add_f32_dpp v42, v42, v42 quad_perm:[2,3,0,1] row_mask:0xf bank_mask:0xf bound_ctrl:1
	s_nop 1
	v_add_f32_dpp v42, v42, v42 row_half_mirror row_mask:0xf bank_mask:0xf bound_ctrl:1
	s_nop 1
	v_add_f32_dpp v42, v42, v42 row_mirror row_mask:0xf bank_mask:0xf bound_ctrl:1
	s_nop 1
	v_mov_b32_dpp v53, v42 row_bcast:15 row_mask:0xa bank_mask:0xf
	v_add_f32_e32 v42, v42, v53
	s_nop 1
	v_mov_b32_dpp v56, v42 row_bcast:31 row_mask:0xc bank_mask:0xf
	v_add_f32_e32 v42, v42, v56
	s_nop 0
	v_readlane_b32 s7, v42, 63
	s_nop 1
	v_fma_f32 v42, s7, v23, v22
	v_mul_f32_e32 v43, 0x4b800000, v42
	v_cmp_gt_f32_e32 vcc, s6, v42
	s_nop 1
	v_cndmask_b32_e32 v42, v42, v43, vcc
	v_rsq_f32_e32 v42, v42
	s_nop 0
	v_mul_f32_e32 v43, 0x45800000, v42
	v_cndmask_b32_e32 v42, v42, v43, vcc
	v_pk_mul_f32 v[64:65], v[64:65], v[42:43] op_sel_hi:[1,0]
	v_pk_mul_f32 v[66:67], v[66:67], v[42:43] op_sel_hi:[1,0]
	v_pk_mul_f32 v[68:69], v[68:69], v[42:43] op_sel_hi:[1,0]
	v_pk_mul_f32 v[70:71], v[70:71], v[42:43] op_sel_hi:[1,0]
	v_pk_mul_f32 v[72:73], v[72:73], v[42:43] op_sel_hi:[1,0]
	v_pk_mul_f32 v[74:75], v[74:75], v[42:43] op_sel_hi:[1,0]
	v_pk_mul_f32 v[76:77], v[76:77], v[42:43] op_sel_hi:[1,0]
	v_pk_mul_f32 v[78:79], v[78:79], v[42:43] op_sel_hi:[1,0]
	v_pk_mul_f32 v[66:67], v[2:3], v[66:67]
	v_pk_mul_f32 v[64:65], v[0:1], v[64:65]
	v_pk_mul_f32 v[70:71], v[6:7], v[70:71]
	v_pk_mul_f32 v[68:69], v[4:5], v[68:69]
	v_pk_mul_f32 v[74:75], v[10:11], v[74:75]
	v_pk_mul_f32 v[72:73], v[8:9], v[72:73]
	v_pk_mul_f32 v[78:79], v[14:15], v[78:79]
	v_pk_mul_f32 v[76:77], v[12:13], v[76:77]
	global_store_dwordx4 v[40:41], v[64:67], off
	global_store_dwordx4 v[40:41], v[68:71], off offset:1024
	global_store_dwordx4 v[40:41], v[72:75], off offset:2048
	global_store_dwordx4 v[40:41], v[76:79], off offset:3072
	v_mov_b32_e32 v53, 0
	v_mov_b32_e32 v56, 0
	s_add_i32 s8, s4, s1
	s_ashr_i32 s9, s8, 31
	s_lshl_b64 s[8:9], s[8:9], 12
	v_lshl_add_u64 v[40:41], v[16:17], 0, s[8:9]
	s_add_i32 s1, s1, 2
	s_cmp_eq_u32 s1, 16
	s_waitcnt vmcnt(15)
	v_pk_mul_f32 v[42:43], v[82:83], v[82:83]
	v_pk_mul_f32 v[44:45], v[80:81], v[80:81]
	s_waitcnt vmcnt(14)
	v_pk_mul_f32 v[46:47], v[86:87], v[86:87]
	v_pk_mul_f32 v[48:49], v[84:85], v[84:85]
	v_pk_mov_b32 v[54:55], v[44:45], v[42:43] op_sel:[1,0]
	v_mov_b32_e32 v45, v43
	v_pk_mov_b32 v[42:43], v[48:49], v[46:47] op_sel:[1,0]
	v_mov_b32_e32 v49, v47
	s_waitcnt vmcnt(12)
	v_mul_f32_e32 v50, v93, v93
	v_mul_f32_e32 v52, v95, v95
	v_pk_add_f32 v[44:45], v[54:55], v[44:45]
	v_pk_add_f32 v[42:43], v[42:43], v[48:49]
	v_mul_f32_e32 v57, v88, v88
	v_mul_f32_e32 v58, v89, v89
	v_mul_f32_e32 v59, v90, v90
	v_mul_f32_e32 v60, v91, v91
	v_pk_fma_f32 v[46:47], v[92:93], v[92:93], v[50:51] op_sel_hi:[1,1,0]
	v_pk_fma_f32 v[50:51], v[94:95], v[94:95], v[52:53] op_sel_hi:[1,1,0]
	v_pk_add_f32 v[44:45], v[44:45], v[44:45] op_sel:[0,1] op_sel_hi:[1,0]
	v_pk_add_f32 v[42:43], v[42:43], v[42:43] op_sel:[0,1] op_sel_hi:[1,0]
	v_mov_b32_e32 v47, v59
	v_mov_b32_e32 v51, v60
	v_mov_b32_e32 v45, v57
	v_mov_b32_e32 v43, v58
	v_pk_add_f32 v[46:47], v[46:47], v[50:51]
	v_pk_add_f32 v[42:43], v[44:45], v[42:43]
	s_nop 0
	v_pk_add_f32 v[42:43], v[42:43], v[46:47]
	s_nop 0
	v_add_f32_e32 v42, v42, v43
	s_nop 1
	v_add_f32_dpp v42, v42, v42 quad_perm:[1,0,3,2] row_mask:0xf bank_mask:0xf bound_ctrl:1
	s_nop 1
	v_add_f32_dpp v42, v42, v42 quad_perm:[2,3,0,1] row_mask:0xf bank_mask:0xf bound_ctrl:1
	s_nop 1
	v_add_f32_dpp v42, v42, v42 row_half_mirror row_mask:0xf bank_mask:0xf bound_ctrl:1
	s_nop 1
	v_add_f32_dpp v42, v42, v42 row_mirror row_mask:0xf bank_mask:0xf bound_ctrl:1
	s_nop 1
	v_mov_b32_dpp v53, v42 row_bcast:15 row_mask:0xa bank_mask:0xf
	v_add_f32_e32 v42, v42, v53
	v_mov_b32_e32 v53, 0
	s_nop 0
	v_mov_b32_dpp v56, v42 row_bcast:31 row_mask:0xc bank_mask:0xf
	v_add_f32_e32 v42, v42, v56
	v_mov_b32_e32 v56, 0
	v_readlane_b32 s7, v42, 63
	s_nop 1
	v_fma_f32 v42, s7, v23, v22
	v_mul_f32_e32 v43, 0x4b800000, v42
	v_cmp_gt_f32_e32 vcc, s6, v42
	s_nop 1
	v_cndmask_b32_e32 v42, v42, v43, vcc
	v_rsq_f32_e32 v42, v42
	s_nop 0
	v_mul_f32_e32 v43, 0x45800000, v42
	v_cndmask_b32_e32 v42, v42, v43, vcc
	v_pk_mul_f32 v[80:81], v[80:81], v[42:43] op_sel_hi:[1,0]
	v_pk_mul_f32 v[82:83], v[82:83], v[42:43] op_sel_hi:[1,0]
	v_pk_mul_f32 v[84:85], v[84:85], v[42:43] op_sel_hi:[1,0]
	v_pk_mul_f32 v[86:87], v[86:87], v[42:43] op_sel_hi:[1,0]
	v_pk_mul_f32 v[92:93], v[92:93], v[42:43] op_sel_hi:[1,0]
	v_pk_mul_f32 v[94:95], v[94:95], v[42:43] op_sel_hi:[1,0]
	v_pk_mul_f32 v[44:45], v[88:89], v[42:43] op_sel_hi:[1,0]
	v_pk_mul_f32 v[42:43], v[90:91], v[42:43] op_sel_hi:[1,0]
	v_pk_mul_f32 v[82:83], v[2:3], v[82:83]
	v_pk_mul_f32 v[80:81], v[0:1], v[80:81]
	v_pk_mul_f32 v[86:87], v[6:7], v[86:87]
	v_pk_mul_f32 v[84:85], v[4:5], v[84:85]
	v_pk_mul_f32 v[90:91], v[10:11], v[94:95]
	v_pk_mul_f32 v[88:89], v[8:9], v[92:93]
	v_pk_mul_f32 v[94:95], v[14:15], v[42:43]
	v_pk_mul_f32 v[92:93], v[12:13], v[44:45]
	global_store_dwordx4 v[20:21], v[80:83], off offset:-2048
	global_store_dwordx4 v[20:21], v[84:87], off offset:-1024
	global_store_dwordx4 v[20:21], v[88:91], off
	global_store_dwordx4 v[20:21], v[92:95], off offset:1024
	v_lshl_add_u64 v[20:21], v[20:21], 0, s[2:3]
	s_waitcnt vmcnt(15)
; __device__ __forceinline__ void final_norm_phase(const Ctx& X, float* out, const float* g) {
;     ...
;         for (int r = 0; r < 16; ++r) { float* xr = out + (size_t)(ch * 16 + r) * DM + X.lane * 4;
;             f32x4 v[4]; float ss = 0.f;
; #pragma unroll
;             for (int j = 0; j < 4; ++j) { v[j] = *(const f32x4*)(xr + 256 * j); ss += (v[j].x * v[j].x + v[j].y * v[j].y) + (v[j].z * v[j].z + v[j].w * v[j].w); }
;             const float rstd = rsqrtf(wave_sum(ss) * (1.f / DM) + EPS);
; #pragma unroll
;             for (int j = 0; j < 4; ++j) *(f32x4*)(xr + 256 * j) = v[j] * rstd * gv[j]; }
	v_pk_mul_f32 v[42:43], v[98:99], v[98:99]
	v_pk_mul_f32 v[44:45], v[96:97], v[96:97]
	s_waitcnt vmcnt(14)
	v_pk_mul_f32 v[46:47], v[102:103], v[102:103]
	v_pk_mul_f32 v[48:49], v[100:101], v[100:101]
	v_pk_mov_b32 v[54:55], v[44:45], v[42:43] op_sel:[1,0]
	v_mov_b32_e32 v45, v43
	v_pk_mov_b32 v[42:43], v[48:49], v[46:47] op_sel:[1,0]
	v_mov_b32_e32 v49, v47
	s_waitcnt vmcnt(13)
	v_mul_f32_e32 v50, v105, v105
	v_mul_f32_e32 v52, v107, v107
	v_pk_add_f32 v[44:45], v[54:55], v[44:45]
	v_pk_add_f32 v[42:43], v[42:43], v[48:49]
	s_waitcnt vmcnt(12)
	v_mul_f32_e32 v57, v108, v108
	v_mul_f32_e32 v58, v109, v109
	v_mul_f32_e32 v59, v110, v110
	v_mul_f32_e32 v60, v111, v111
	v_pk_fma_f32 v[46:47], v[104:105], v[104:105], v[50:51] op_sel_hi:[1,1,0]
	v_pk_fma_f32 v[50:51], v[106:107], v[106:107], v[52:53] op_sel_hi:[1,1,0]
	v_pk_add_f32 v[44:45], v[44:45], v[44:45] op_sel:[0,1] op_sel_hi:[1,0]
	v_pk_add_f32 v[42:43], v[42:43], v[42:43] op_sel:[0,1] op_sel_hi:[1,0]
	v_mov_b32_e32 v47, v59
	v_mov_b32_e32 v51, v60
	v_mov_b32_e32 v45, v57
	v_mov_b32_e32 v43, v58
	v_pk_add_f32 v[46:47], v[46:47], v[50:51]
	v_pk_add_f32 v[42:43], v[44:45], v[42:43]
	s_nop 0
	v_pk_add_f32 v[42:43], v[42:43], v[46:47]
	s_nop 0
	v_add_f32_e32 v42, v42, v43
	s_nop 1
	v_add_f32_dpp v42, v42, v42 quad_perm:[1,0,3,2] row_mask:0xf bank_mask:0xf bound_ctrl:1
	s_nop 1
	v_add_f32_dpp v42, v42, v42 quad_perm:[2,3,0,1] row_mask:0xf bank_mask:0xf bound_ctrl:1
	s_nop 1
	v_add_f32_dpp v42, v42, v42 row_half_mirror row_mask:0xf bank_mask:0xf bound_ctrl:1
	s_nop 1
	v_add_f32_dpp v42, v42, v42 row_mirror row_mask:0xf bank_mask:0xf bound_ctrl:1
	s_nop 1
	v_mov_b32_dpp v53, v42 row_bcast:15 row_mask:0xa bank_mask:0xf
	v_add_f32_e32 v42, v42, v53
	s_nop 1
	v_mov_b32_dpp v56, v42 row_bcast:31 row_mask:0xc bank_mask:0xf
	v_add_f32_e32 v42, v42, v56
	s_nop 0
	v_readlane_b32 s7, v42, 63
	s_nop 1
	v_fma_f32 v42, s7, v23, v22
	v_mul_f32_e32 v43, 0x4b800000, v42
	v_cmp_gt_f32_e32 vcc, s6, v42
	s_nop 1
	v_cndmask_b32_e32 v42, v42, v43, vcc
	v_rsq_f32_e32 v42, v42
	s_nop 0
	v_mul_f32_e32 v43, 0x45800000, v42
	v_cndmask_b32_e32 v42, v42, v43, vcc
	v_pk_mul_f32 v[96:97], v[96:97], v[42:43] op_sel_hi:[1,0]
	v_pk_mul_f32 v[98:99], v[98:99], v[42:43] op_sel_hi:[1,0]
	v_pk_mul_f32 v[100:101], v[100:101], v[42:43] op_sel_hi:[1,0]
	v_pk_mul_f32 v[102:103], v[102:103], v[42:43] op_sel_hi:[1,0]
	v_pk_mul_f32 v[104:105], v[104:105], v[42:43] op_sel_hi:[1,0]
	v_pk_mul_f32 v[106:107], v[106:107], v[42:43] op_sel_hi:[1,0]
	v_pk_mul_f32 v[108:109], v[108:109], v[42:43] op_sel_hi:[1,0]
	v_pk_mul_f32 v[110:111], v[110:111], v[42:43] op_sel_hi:[1,0]
	v_pk_mul_f32 v[98:99], v[2:3], v[98:99]
	v_pk_mul_f32 v[96:97], v[0:1], v[96:97]
	v_pk_mul_f32 v[102:103], v[6:7], v[102:103]
	v_pk_mul_f32 v[100:101], v[4:5], v[100:101]
	v_pk_mul_f32 v[106:107], v[10:11], v[106:107]
	v_pk_mul_f32 v[104:105], v[8:9], v[104:105]
	v_pk_mul_f32 v[110:111], v[14:15], v[110:111]
	v_pk_mul_f32 v[108:109], v[12:13], v[108:109]
	global_store_dwordx4 v[40:41], v[96:99], off
	global_store_dwordx4 v[40:41], v[100:103], off offset:1024
	global_store_dwordx4 v[40:41], v[104:107], off offset:2048
	global_store_dwordx4 v[40:41], v[108:111], off offset:3072
	s_cbranch_scc0 .LBB0_885
	s_add_i32 s86, s86, s87
	s_add_i32 s4, s4, s5
	s_add_i32 s0, s0, s5
	s_cmpk_gt_i32 s86, 0x17ff
	s_cbranch_scc0 .LBB0_884
